# v56: v55 + single V-fragment address per tile + out-proj K-loop tail pointer steps/counters between the MFMAs of the last section (7.11-style)
# baseline (speedup 1.0000x reference)
; #define G_STAGE(bufoff, gbase, voff) do { _Pragma("unroll") for (int _i = 0; _i < 2; ++_i) \
;     __builtin_amdgcn_global_load_lds((const unsigned*)((const char*)(gbase) + (voff)[_i]), (LAS unsigned*)(lds + (bufoff) + ldsw + _i * 8192), 16, 0, 0); } while (0)
; #define G_LDA(dst, b, h) do { _Pragma("unroll") for (int m = 0; m < 4; ++m) _Pragma("unroll") for (int k = 0; k < 2; ++k) dst[m][k] = *(const LAS bf16x8*)(lds + G_SA(b, h) + aoff + m * 2048 + k * 1024); } while (0)
; #define G_LDB(dst, b, h) do { _Pragma("unroll") for (int n = 0; n < 2; ++n) _Pragma("unroll") for (int k = 0; k < 2; ++k) dst[n][k] = *(const LAS bf16x8*)(lds + G_SB(b, h) + boff + n * 2048 + k * 1024); } while (0)
; #define G_MMA(ai, bj, At, Bt) do { __builtin_amdgcn_s_setprio(1); _Pragma("unroll") for (int m = 0; m < 4; ++m) _Pragma("unroll") for (int n = 0; n < 2; ++n) _Pragma("unroll") for (int k = 0; k < 2; ++k) \
;     acc[ai][bj][m][n] = __builtin_amdgcn_mfma_f32_16x16x32_bf16(Bt[n][k], At[m][k], acc[ai][bj][m][n], 0, 0, 0); __builtin_amdgcn_s_setprio(0); } while (0)
; #define G_WAIT_L(n) asm volatile("s_waitcnt lgkmcnt(" #n ")" ::: "memory")
; template <int GP> DI void gemm_phase(const Params& p, int l, int which, char* smem, int wv) {
;     ...
;     const char* nA = has_next ? (const char*)Aglob + (size_t)nmt * tstep + (size_t)nk0 * 2 : cA;
;     const char* nB = has_next ? (const char*)Wt + (size_t)nnt * tstep + (size_t)nk0 * 2 : cB;
;     const bool n32 = has_next ? ((!which) && (nnt < 4)) : c32;
;     for (int t = 0; t < cnk; t += 2) {
;       const bool last = (t == cnk - 2);
;       const char* a1 = cA + (size_t)(t + 1) * kstep;
;       const char* a2 = last ? nA : cA + (size_t)(t + 2) * kstep; const char* b2 = last ? nB : cB + (size_t)(t + 2) * kstep;
;       const char* a3 = a2 + kstep; const char* b3 = b2 + kstep;
;       if (last) {
; #pragma unroll
;         for (int i = 0; i < 2; ++i) { vb0[i] = voffB(i, 0, n32); vb1[i] = voffB(i, 1, n32); }
;       }
;       G_LDB(B0, 0, 0); G_SCHED; G_LDA(At, 0, 0); G_STAGE(G_SA(1, 1), a1 + hstep, voffA);
;       G_WAIT_L(8); G_BAR; G_WAIT_L(0); G_MMA(0, 0, At, B0); G_BAR; G_SCHED;
;       G_LDB(B1, 0, 1); G_STAGE(G_SB(0, 0), b2, vb0);
;       G_BAR; G_WAIT_L(0); G_MMA(0, 1, At, B1); G_BAR;
;       G_LDA(At, 0, 1); G_STAGE(G_SA(0, 0), a2, voffA);
;       G_BAR; G_WAIT_L(0); G_MMA(1, 0, At, B0); G_BAR; G_SCHED;
.LBB0_149:
	v_add_u32_e32 v135, 0x10000, v166
	s_add_u32 s61, s8, s26
	ds_read_b128 v[168:171], v135
	ds_read_b128 v[172:175], v135 offset:1024
	ds_read_b128 v[176:179], v135 offset:2048
	ds_read_b128 v[180:183], v135 offset:3072
	s_addc_u32 s62, s9, s27
	s_and_b64 s[30:31], s[28:29], exec
	s_cselect_b32 s31, s11, s62
	s_cselect_b32 s30, s57, s61
	s_add_u32 s61, s6, s26
	s_addc_u32 s62, s7, s27
	s_and_b64 s[28:29], s[28:29], exec
	s_cselect_b32 s28, s59, s61
	s_cselect_b32 s29, s58, s62
	s_mov_b32 m0, s53
	v_lshl_add_u64 v[216:217], s[8:9], 0, v[162:163]
	ds_read_b128 v[184:187], v165
	ds_read_b128 v[188:191], v165 offset:1024
	ds_read_b128 v[192:195], v165 offset:2048
	ds_read_b128 v[196:199], v165 offset:3072
	ds_read_b128 v[200:203], v165 offset:4096
	ds_read_b128 v[204:207], v165 offset:5120
	ds_read_b128 v[208:211], v165 offset:6144
	ds_read_b128 v[212:215], v165 offset:7168
	global_load_lds_dwordx4 v[216:217], off
	v_lshl_add_u64 v[216:217], s[8:9], 0, v[160:161]
	s_mov_b32 m0, s54
	s_nop 0
	global_load_lds_dwordx4 v[216:217], off
	s_waitcnt lgkmcnt(8)
	s_barrier
	s_waitcnt lgkmcnt(0)
	v_mfma_f32_16x16x32_bf16 v[62:65], v[168:171], v[184:187], v[62:65]
	v_mfma_f32_16x16x32_bf16 v[58:61], v[176:179], v[184:187], v[58:61]
	v_mfma_f32_16x16x32_bf16 v[54:57], v[168:171], v[192:195], v[54:57]
	v_mfma_f32_16x16x32_bf16 v[50:53], v[176:179], v[192:195], v[50:53]
	v_mfma_f32_16x16x32_bf16 v[46:49], v[168:171], v[200:203], v[46:49]
	v_mfma_f32_16x16x32_bf16 v[42:45], v[176:179], v[200:203], v[42:45]
	v_mfma_f32_16x16x32_bf16 v[38:41], v[168:171], v[208:211], v[38:41]
	v_mfma_f32_16x16x32_bf16 v[34:37], v[176:179], v[208:211], v[34:37]
	v_mfma_f32_16x16x32_bf16 v[62:65], v[172:175], v[188:191], v[62:65]
	v_mfma_f32_16x16x32_bf16 v[58:61], v[180:183], v[188:191], v[58:61]
	v_mfma_f32_16x16x32_bf16 v[54:57], v[172:175], v[196:199], v[54:57]
	v_mfma_f32_16x16x32_bf16 v[50:53], v[180:183], v[196:199], v[50:53]
	v_mfma_f32_16x16x32_bf16 v[46:49], v[172:175], v[204:207], v[46:49]
	v_mfma_f32_16x16x32_bf16 v[42:45], v[180:183], v[204:207], v[42:45]
	v_mfma_f32_16x16x32_bf16 v[38:41], v[172:175], v[212:215], v[38:41]
	v_mfma_f32_16x16x32_bf16 v[34:37], v[180:183], v[212:215], v[34:37]
	s_barrier
	s_mov_b32 m0, s1
	v_add_u32_e32 v135, 0x14000, v166
	ds_read_b128 v[216:219], v135
	ds_read_b128 v[220:223], v135 offset:1024
	ds_read_b128 v[224:227], v135 offset:2048
	ds_read_b128 v[238:241], v135 offset:3072
	global_load_lds_dwordx4 v0, s[28:29]
	s_mov_b32 m0, s3
	v_mov_b32_e32 v137, v1
	global_load_lds_dwordx4 v136, s[28:29]
	s_barrier
	s_waitcnt lgkmcnt(0)
	v_lshl_add_u64 v[228:229], s[28:29], 0, v[0:1]
	v_lshl_add_u64 v[234:235], s[28:29], 0, v[136:137]
	s_waitcnt lgkmcnt(0)
	v_mfma_f32_16x16x32_bf16 v[30:33], v[216:219], v[184:187], v[30:33]
	v_mfma_f32_16x16x32_bf16 v[26:29], v[224:227], v[184:187], v[26:29]
	v_mfma_f32_16x16x32_bf16 v[22:25], v[216:219], v[192:195], v[22:25]
	v_mfma_f32_16x16x32_bf16 v[18:21], v[224:227], v[192:195], v[18:21]
	v_mfma_f32_16x16x32_bf16 v[14:17], v[216:219], v[200:203], v[14:17]
	v_mfma_f32_16x16x32_bf16 v[10:13], v[224:227], v[200:203], v[10:13]
	v_mfma_f32_16x16x32_bf16 v[6:9], v[216:219], v[208:211], v[6:9]
	v_mfma_f32_16x16x32_bf16 v[2:5], v[224:227], v[208:211], v[2:5]
	v_mfma_f32_16x16x32_bf16 v[30:33], v[220:223], v[188:191], v[30:33]
	v_mfma_f32_16x16x32_bf16 v[26:29], v[238:241], v[188:191], v[26:29]
	v_mfma_f32_16x16x32_bf16 v[22:25], v[220:223], v[196:199], v[22:25]
	v_mfma_f32_16x16x32_bf16 v[18:21], v[238:241], v[196:199], v[18:21]
	v_mfma_f32_16x16x32_bf16 v[14:17], v[220:223], v[204:207], v[14:17]
	v_mfma_f32_16x16x32_bf16 v[10:13], v[238:241], v[204:207], v[10:13]
	v_mfma_f32_16x16x32_bf16 v[6:9], v[220:223], v[212:215], v[6:9]
	v_mfma_f32_16x16x32_bf16 v[2:5], v[238:241], v[212:215], v[2:5]
	s_mov_b32 m0, s38
	v_lshl_add_u64 v[242:243], s[30:31], 0, v[130:131]
	s_barrier
	ds_read_b128 v[184:187], v165 offset:16384
	ds_read_b128 v[188:191], v165 offset:17408
	ds_read_b128 v[192:195], v165 offset:18432
	ds_read_b128 v[196:199], v165 offset:19456
	ds_read_b128 v[200:203], v165 offset:20480
	ds_read_b128 v[204:207], v165 offset:21504
	ds_read_b128 v[208:211], v165 offset:22528
	ds_read_b128 v[212:215], v165 offset:23552
	global_load_lds_dwordx4 v[242:243], off
	v_lshl_add_u64 v[244:245], s[30:31], 0, v[132:133]
	s_mov_b32 m0, s5
	s_nop 0
	global_load_lds_dwordx4 v[244:245], off
	s_barrier
	s_waitcnt lgkmcnt(0)
	v_mfma_f32_16x16x32_bf16 v[66:69], v[168:171], v[184:187], v[66:69]
	v_mfma_f32_16x16x32_bf16 v[70:73], v[176:179], v[184:187], v[70:73]
	v_mfma_f32_16x16x32_bf16 v[74:77], v[168:171], v[192:195], v[74:77]
	v_mfma_f32_16x16x32_bf16 v[78:81], v[176:179], v[192:195], v[78:81]
	v_mfma_f32_16x16x32_bf16 v[82:85], v[168:171], v[200:203], v[82:85]
	v_mfma_f32_16x16x32_bf16 v[86:89], v[176:179], v[200:203], v[86:89]
	v_mfma_f32_16x16x32_bf16 v[90:93], v[168:171], v[208:211], v[90:93]
	v_mfma_f32_16x16x32_bf16 v[98:101], v[176:179], v[208:211], v[98:101]
	v_mfma_f32_16x16x32_bf16 v[66:69], v[172:175], v[188:191], v[66:69]
	v_mfma_f32_16x16x32_bf16 v[70:73], v[180:183], v[188:191], v[70:73]
	v_mfma_f32_16x16x32_bf16 v[74:77], v[172:175], v[196:199], v[74:77]
	v_mfma_f32_16x16x32_bf16 v[78:81], v[180:183], v[196:199], v[78:81]
	v_mfma_f32_16x16x32_bf16 v[82:85], v[172:175], v[204:207], v[82:85]
	v_mfma_f32_16x16x32_bf16 v[86:89], v[180:183], v[204:207], v[86:89]
	v_mfma_f32_16x16x32_bf16 v[90:93], v[172:175], v[212:215], v[90:93]
	v_mfma_f32_16x16x32_bf16 v[98:101], v[180:183], v[212:215], v[98:101]
	s_barrier
; #define G_STAGE(bufoff, gbase, voff) do { _Pragma("unroll") for (int _i = 0; _i < 2; ++_i) \
;     __builtin_amdgcn_global_load_lds((const unsigned*)((const char*)(gbase) + (voff)[_i]), (LAS unsigned*)(lds + (bufoff) + ldsw + _i * 8192), 16, 0, 0); } while (0)
; #define G_LDA(dst, b, h) do { _Pragma("unroll") for (int m = 0; m < 4; ++m) _Pragma("unroll") for (int k = 0; k < 2; ++k) dst[m][k] = *(const LAS bf16x8*)(lds + G_SA(b, h) + aoff + m * 2048 + k * 1024); } while (0)
; #define G_LDB(dst, b, h) do { _Pragma("unroll") for (int n = 0; n < 2; ++n) _Pragma("unroll") for (int k = 0; k < 2; ++k) dst[n][k] = *(const LAS bf16x8*)(lds + G_SB(b, h) + boff + n * 2048 + k * 1024); } while (0)
; #define G_MMA(ai, bj, At, Bt) do { __builtin_amdgcn_s_setprio(1); _Pragma("unroll") for (int m = 0; m < 4; ++m) _Pragma("unroll") for (int n = 0; n < 2; ++n) _Pragma("unroll") for (int k = 0; k < 2; ++k) \
;     acc[ai][bj][m][n] = __builtin_amdgcn_mfma_f32_16x16x32_bf16(Bt[n][k], At[m][k], acc[ai][bj][m][n], 0, 0, 0); __builtin_amdgcn_s_setprio(0); } while (0)
; #define G_WAIT_V(n) asm volatile("s_waitcnt vmcnt(" #n ")" ::: "memory")
; #define G_WAIT_L(n) asm volatile("s_waitcnt lgkmcnt(" #n ")" ::: "memory")
; #define G_BAR __builtin_amdgcn_s_barrier()
; #define G_SCHED __builtin_amdgcn_sched_barrier(0)
; template <int GP> DI void gemm_phase(const Params& p, int l, int which, char* smem, int wv) {
;     ...
;       G_LDB(B0, 0, 0); G_SCHED; G_LDA(At, 0, 0); G_STAGE(G_SA(1, 1), a1 + hstep, voffA);
;       G_WAIT_L(8); G_BAR; G_WAIT_L(0); G_MMA(0, 0, At, B0); G_BAR; G_SCHED;
;       G_LDB(B1, 0, 1); G_STAGE(G_SB(0, 0), b2, vb0);
;       G_BAR; G_WAIT_L(0); G_MMA(0, 1, At, B1); G_BAR;
;       G_LDA(At, 0, 1); G_STAGE(G_SA(0, 0), a2, voffA);
;       G_BAR; G_WAIT_L(0); G_MMA(1, 0, At, B0); G_BAR; G_SCHED;
;       G_STAGE(G_SB(0, 1), b2, vb1);
;       G_WAIT_V(6); G_BAR; G_MMA(1, 1, At, B1); G_BAR;
;       G_LDB(B0, 1, 0); G_SCHED; G_LDA(At, 1, 0); G_STAGE(G_SA(0, 1), a2 + hstep, voffA);
;       G_WAIT_L(8); G_BAR; G_WAIT_L(0); G_MMA(0, 0, At, B0); G_BAR; G_SCHED;
;       G_LDB(B1, 1, 1); G_STAGE(G_SB(1, 0), b3, vb0);
;       G_BAR; G_WAIT_L(0); G_MMA(0, 1, At, B1); G_BAR;
;       G_LDA(At, 1, 1); G_STAGE(G_SA(1, 0), a3, voffA);
;       G_BAR; G_WAIT_L(0); G_MMA(1, 0, At, B0); G_BAR; G_SCHED;
;       G_STAGE(G_SB(1, 1), b3, vb1);
;       G_WAIT_V(6); G_BAR; G_MMA(1, 1, At, B1); G_BAR;
	s_mov_b32 m0, s41
	v_mov_b32_e32 v135, v1
	global_load_lds_dwordx4 v134, s[28:29]
	s_mov_b32 m0, s42
	v_mov_b32_e32 v155, v1
	global_load_lds_dwordx4 v154, s[28:29]
	s_waitcnt vmcnt(6)
	v_lshl_add_u64 v[246:247], s[28:29], 0, v[134:135]
	v_lshl_add_u64 v[248:249], s[28:29], 0, v[154:155]
	s_barrier
	v_mfma_f32_16x16x32_bf16 v[94:97], v[216:219], v[184:187], v[94:97]
	v_mfma_f32_16x16x32_bf16 v[102:105], v[224:227], v[184:187], v[102:105]
	v_mfma_f32_16x16x32_bf16 v[106:109], v[216:219], v[192:195], v[106:109]
	v_mfma_f32_16x16x32_bf16 v[110:113], v[224:227], v[192:195], v[110:113]
	v_mfma_f32_16x16x32_bf16 v[114:117], v[216:219], v[200:203], v[114:117]
	v_mfma_f32_16x16x32_bf16 v[118:121], v[224:227], v[200:203], v[118:121]
	v_mfma_f32_16x16x32_bf16 v[122:125], v[216:219], v[208:211], v[122:125]
	v_mfma_f32_16x16x32_bf16 v[126:129], v[224:227], v[208:211], v[126:129]
	v_mfma_f32_16x16x32_bf16 v[94:97], v[220:223], v[188:191], v[94:97]
	v_mfma_f32_16x16x32_bf16 v[102:105], v[238:241], v[188:191], v[102:105]
	v_mfma_f32_16x16x32_bf16 v[106:109], v[220:223], v[196:199], v[106:109]
	v_mfma_f32_16x16x32_bf16 v[110:113], v[238:241], v[196:199], v[110:113]
	v_mfma_f32_16x16x32_bf16 v[114:117], v[220:223], v[204:207], v[114:117]
	v_mfma_f32_16x16x32_bf16 v[118:121], v[238:241], v[204:207], v[118:121]
	v_mfma_f32_16x16x32_bf16 v[122:125], v[220:223], v[212:215], v[122:125]
	v_mfma_f32_16x16x32_bf16 v[126:129], v[238:241], v[212:215], v[126:129]
	v_add_u32_e32 v135, 0x18000, v166
	s_barrier
	ds_read_b128 v[168:171], v135
	ds_read_b128 v[172:175], v135 offset:1024
	ds_read_b128 v[176:179], v135 offset:2048
	ds_read_b128 v[180:183], v135 offset:3072
	s_add_u32 s28, s30, 0x80000
	s_addc_u32 s29, s31, 0
	s_mov_b32 m0, s43
	v_lshl_add_u64 v[216:217], s[28:29], 0, v[130:131]
	ds_read_b128 v[184:187], v165 offset:32768
	ds_read_b128 v[188:191], v165 offset:33792
	ds_read_b128 v[192:195], v165 offset:34816
	ds_read_b128 v[196:199], v165 offset:35840
	ds_read_b128 v[200:203], v165 offset:36864
	ds_read_b128 v[204:207], v165 offset:37888
	ds_read_b128 v[208:211], v165 offset:38912
	ds_read_b128 v[212:215], v165 offset:39936
	global_load_lds_dwordx4 v[216:217], off
	v_lshl_add_u64 v[216:217], s[28:29], 0, v[132:133]
	s_mov_b32 m0, s44
	s_nop 0
	global_load_lds_dwordx4 v[216:217], off
	s_waitcnt lgkmcnt(8)
	s_barrier
	s_waitcnt lgkmcnt(0)
	v_mfma_f32_16x16x32_bf16 v[62:65], v[168:171], v[184:187], v[62:65]
	v_mfma_f32_16x16x32_bf16 v[58:61], v[176:179], v[184:187], v[58:61]
	v_mfma_f32_16x16x32_bf16 v[54:57], v[168:171], v[192:195], v[54:57]
	v_mfma_f32_16x16x32_bf16 v[50:53], v[176:179], v[192:195], v[50:53]
	v_mfma_f32_16x16x32_bf16 v[46:49], v[168:171], v[200:203], v[46:49]
	v_mfma_f32_16x16x32_bf16 v[42:45], v[176:179], v[200:203], v[42:45]
	v_mfma_f32_16x16x32_bf16 v[38:41], v[168:171], v[208:211], v[38:41]
	v_mfma_f32_16x16x32_bf16 v[34:37], v[176:179], v[208:211], v[34:37]
	v_mfma_f32_16x16x32_bf16 v[62:65], v[172:175], v[188:191], v[62:65]
	v_mfma_f32_16x16x32_bf16 v[58:61], v[180:183], v[188:191], v[58:61]
	v_mfma_f32_16x16x32_bf16 v[54:57], v[172:175], v[196:199], v[54:57]
	v_mfma_f32_16x16x32_bf16 v[50:53], v[180:183], v[196:199], v[50:53]
	v_mfma_f32_16x16x32_bf16 v[46:49], v[172:175], v[204:207], v[46:49]
	v_mfma_f32_16x16x32_bf16 v[42:45], v[180:183], v[204:207], v[42:45]
	v_mfma_f32_16x16x32_bf16 v[38:41], v[172:175], v[212:215], v[38:41]
	v_mfma_f32_16x16x32_bf16 v[34:37], v[180:183], v[212:215], v[34:37]
	s_barrier
	s_mov_b32 m0, s45
	v_add_u32_e32 v135, 0x1c000, v166
	v_lshl_add_u64 v[228:229], v[228:229], 0, s[74:75]
	ds_read_b128 v[216:219], v135
	ds_read_b128 v[220:223], v135 offset:1024
	ds_read_b128 v[224:227], v135 offset:2048
	ds_read_b128 v[238:241], v135 offset:3072
	global_load_lds_dwordx4 v[228:229], off
	v_lshl_add_u64 v[228:229], v[234:235], 0, s[74:75]
	s_mov_b32 m0, s46
	s_nop 0
	global_load_lds_dwordx4 v[228:229], off
	s_barrier
; #define G_STAGE(bufoff, gbase, voff) do { _Pragma("unroll") for (int _i = 0; _i < 2; ++_i) \
;     __builtin_amdgcn_global_load_lds((const unsigned*)((const char*)(gbase) + (voff)[_i]), (LAS unsigned*)(lds + (bufoff) + ldsw + _i * 8192), 16, 0, 0); } while (0)
; #define G_LDA(dst, b, h) do { _Pragma("unroll") for (int m = 0; m < 4; ++m) _Pragma("unroll") for (int k = 0; k < 2; ++k) dst[m][k] = *(const LAS bf16x8*)(lds + G_SA(b, h) + aoff + m * 2048 + k * 1024); } while (0)
; #define G_LDB(dst, b, h) do { _Pragma("unroll") for (int n = 0; n < 2; ++n) _Pragma("unroll") for (int k = 0; k < 2; ++k) dst[n][k] = *(const LAS bf16x8*)(lds + G_SB(b, h) + boff + n * 2048 + k * 1024); } while (0)
; #define G_WAIT_V(n) asm volatile("s_waitcnt vmcnt(" #n ")" ::: "memory")
; #define G_WAIT_L(n) asm volatile("s_waitcnt lgkmcnt(" #n ")" ::: "memory")
; template <int GP> DI void gemm_phase(const Params& p, int l, int which, char* smem, int wv) {
;     ...
;       G_LDB(B0, 0, 0); G_SCHED; G_LDA(At, 0, 0); G_STAGE(G_SA(1, 1), a1 + hstep, voffA);
;       G_WAIT_L(8); G_BAR; G_WAIT_L(0); G_MMA(0, 0, At, B0); G_BAR; G_SCHED;
;       G_LDB(B1, 0, 1); G_STAGE(G_SB(0, 0), b2, vb0);
;       G_BAR; G_WAIT_L(0); G_MMA(0, 1, At, B1); G_BAR;
;       G_LDA(At, 0, 1); G_STAGE(G_SA(0, 0), a2, voffA);
;       G_BAR; G_WAIT_L(0); G_MMA(1, 0, At, B0); G_BAR; G_SCHED;
;       G_STAGE(G_SB(0, 1), b2, vb1);
;       G_WAIT_V(6); G_BAR; G_MMA(1, 1, At, B1); G_BAR;
;       G_LDB(B0, 1, 0); G_SCHED; G_LDA(At, 1, 0); G_STAGE(G_SA(0, 1), a2 + hstep, voffA);
;       G_WAIT_L(8); G_BAR; G_WAIT_L(0); G_MMA(0, 0, At, B0); G_BAR; G_SCHED;
;       G_LDB(B1, 1, 1); G_STAGE(G_SB(1, 0), b3, vb0);
;       G_BAR; G_WAIT_L(0); G_MMA(0, 1, At, B1); G_BAR;
;       G_LDA(At, 1, 1); G_STAGE(G_SA(1, 0), a3, voffA);
;       G_BAR; G_WAIT_L(0); G_MMA(1, 0, At, B0); G_BAR; G_SCHED;
;       G_STAGE(G_SB(1, 1), b3, vb1);
;       G_WAIT_V(6); G_BAR; G_MMA(1, 1, At, B1); G_BAR;
;     ...
;       const int m0 = cmt * 256, n0 = cnt_ * 256;
;       const bool isctx = (cmt % 9) == 0;
;       const int head = wc >> 1;
;       const int n128 = cnt_ * 2 + head;
;       const int rowl0 = wr * 64 + fr;
;       if (which) {
;         const int colb = n0 + head * 128 + (wc & 1) * 32 + fq * 8;
;         u16* ybase = isctx ? p.ypart + ((size_t)(ck0 >> 8) * 1024 + (size_t)(cmt / 9) * 256) * DM : p.y + (size_t)m0 * DM;
	s_waitcnt lgkmcnt(0)
	v_mfma_f32_16x16x32_bf16 v[30:33], v[216:219], v[184:187], v[30:33]
	v_mfma_f32_16x16x32_bf16 v[26:29], v[224:227], v[184:187], v[26:29]
	v_mfma_f32_16x16x32_bf16 v[22:25], v[216:219], v[192:195], v[22:25]
	v_mfma_f32_16x16x32_bf16 v[18:21], v[224:227], v[192:195], v[18:21]
	v_mfma_f32_16x16x32_bf16 v[14:17], v[216:219], v[200:203], v[14:17]
	v_mfma_f32_16x16x32_bf16 v[10:13], v[224:227], v[200:203], v[10:13]
	v_mfma_f32_16x16x32_bf16 v[6:9], v[216:219], v[208:211], v[6:9]
	v_mfma_f32_16x16x32_bf16 v[2:5], v[224:227], v[208:211], v[2:5]
	v_mfma_f32_16x16x32_bf16 v[30:33], v[220:223], v[188:191], v[30:33]
	v_mfma_f32_16x16x32_bf16 v[26:29], v[238:241], v[188:191], v[26:29]
	v_mfma_f32_16x16x32_bf16 v[22:25], v[220:223], v[196:199], v[22:25]
	v_mfma_f32_16x16x32_bf16 v[18:21], v[238:241], v[196:199], v[18:21]
	v_mfma_f32_16x16x32_bf16 v[14:17], v[220:223], v[204:207], v[14:17]
	v_mfma_f32_16x16x32_bf16 v[10:13], v[238:241], v[204:207], v[10:13]
	v_mfma_f32_16x16x32_bf16 v[6:9], v[220:223], v[212:215], v[6:9]
	v_mfma_f32_16x16x32_bf16 v[2:5], v[238:241], v[212:215], v[2:5]
	s_mov_b32 m0, s48
	v_lshl_add_u64 v[228:229], v[242:243], 0, s[74:75]
	s_barrier
	ds_read_b128 v[184:187], v165 offset:49152
	ds_read_b128 v[188:191], v165 offset:50176
	ds_read_b128 v[192:195], v165 offset:51200
	ds_read_b128 v[196:199], v165 offset:52224
	ds_read_b128 v[200:203], v165 offset:53248
	ds_read_b128 v[204:207], v165 offset:54272
	ds_read_b128 v[208:211], v165 offset:55296
	ds_read_b128 v[212:215], v165 offset:56320
	global_load_lds_dwordx4 v[228:229], off
	v_lshl_add_u64 v[228:229], v[244:245], 0, s[74:75]
	s_mov_b32 m0, s49
	s_nop 0
	global_load_lds_dwordx4 v[228:229], off
	s_barrier
	s_waitcnt lgkmcnt(0)
	v_mfma_f32_16x16x32_bf16 v[66:69], v[168:171], v[184:187], v[66:69]
	v_mfma_f32_16x16x32_bf16 v[70:73], v[176:179], v[184:187], v[70:73]
	v_mfma_f32_16x16x32_bf16 v[74:77], v[168:171], v[192:195], v[74:77]
	v_mfma_f32_16x16x32_bf16 v[78:81], v[176:179], v[192:195], v[78:81]
	v_mfma_f32_16x16x32_bf16 v[82:85], v[168:171], v[200:203], v[82:85]
	v_mfma_f32_16x16x32_bf16 v[86:89], v[176:179], v[200:203], v[86:89]
	v_mfma_f32_16x16x32_bf16 v[90:93], v[168:171], v[208:211], v[90:93]
	v_mfma_f32_16x16x32_bf16 v[98:101], v[176:179], v[208:211], v[98:101]
	v_mfma_f32_16x16x32_bf16 v[66:69], v[172:175], v[188:191], v[66:69]
	v_mfma_f32_16x16x32_bf16 v[70:73], v[180:183], v[188:191], v[70:73]
	v_mfma_f32_16x16x32_bf16 v[74:77], v[172:175], v[196:199], v[74:77]
	v_mfma_f32_16x16x32_bf16 v[78:81], v[180:183], v[196:199], v[78:81]
	v_mfma_f32_16x16x32_bf16 v[82:85], v[172:175], v[204:207], v[82:85]
	v_mfma_f32_16x16x32_bf16 v[86:89], v[180:183], v[204:207], v[86:89]
	v_mfma_f32_16x16x32_bf16 v[90:93], v[172:175], v[212:215], v[90:93]
	v_mfma_f32_16x16x32_bf16 v[98:101], v[180:183], v[212:215], v[98:101]
	s_barrier
	s_mov_b32 m0, s50
	v_lshl_add_u64 v[168:169], v[246:247], 0, s[74:75]
	global_load_lds_dwordx4 v[168:169], off
	v_lshl_add_u64 v[168:169], v[248:249], 0, s[74:75]
	s_mov_b32 m0, s52
	s_nop 0
	global_load_lds_dwordx4 v[168:169], off
	s_waitcnt vmcnt(6)
	s_barrier
	v_mfma_f32_16x16x32_bf16 v[94:97], v[216:219], v[184:187], v[94:97]
	v_mfma_f32_16x16x32_bf16 v[102:105], v[224:227], v[184:187], v[102:105]
	s_add_i32 s28, s60, 2
	s_add_u32 s26, s26, 0x100
	s_addc_u32 s27, s27, 0
	v_mfma_f32_16x16x32_bf16 v[106:109], v[216:219], v[192:195], v[106:109]
	v_mfma_f32_16x16x32_bf16 v[110:113], v[224:227], v[192:195], v[110:113]
	v_mfma_f32_16x16x32_bf16 v[114:117], v[216:219], v[200:203], v[114:117]
	v_mfma_f32_16x16x32_bf16 v[118:121], v[224:227], v[200:203], v[118:121]
	v_lshl_add_u64 v[162:163], v[162:163], 0, s[78:79]
	v_mfma_f32_16x16x32_bf16 v[122:125], v[216:219], v[208:211], v[122:125]
	v_mfma_f32_16x16x32_bf16 v[126:129], v[224:227], v[208:211], v[126:129]
	v_mfma_f32_16x16x32_bf16 v[94:97], v[220:223], v[188:191], v[94:97]
	v_mfma_f32_16x16x32_bf16 v[102:105], v[238:241], v[188:191], v[102:105]
	v_lshl_add_u64 v[160:161], v[160:161], 0, s[78:79]
	v_mfma_f32_16x16x32_bf16 v[106:109], v[220:223], v[196:199], v[106:109]
	v_mfma_f32_16x16x32_bf16 v[110:113], v[238:241], v[196:199], v[110:113]
	v_mfma_f32_16x16x32_bf16 v[114:117], v[220:223], v[204:207], v[114:117]
	v_mfma_f32_16x16x32_bf16 v[118:121], v[238:241], v[204:207], v[118:121]
	v_mfma_f32_16x16x32_bf16 v[122:125], v[220:223], v[212:215], v[122:125]
	v_mfma_f32_16x16x32_bf16 v[126:129], v[238:241], v[212:215], v[126:129]
	s_cmp_ge_i32 s60, s36
	s_barrier
	s_cbranch_scc0 .LBB0_147
	s_mul_hi_i32 s11, s2, 0x38e38e39
	s_lshr_b32 s26, s11, 31
	s_ashr_i32 s11, s11, 1
	s_add_i32 s26, s11, s26
	s_mul_i32 s11, s26, 9
	s_sub_i32 s11, s2, s11
	s_cmp_lg_u32 s11, 0
	s_cbranch_scc0 .LBB0_155
	s_lshl_b32 s28, s2, 8
	s_ashr_i32 s29, s28, 31
	s_lshl_b64 s[28:29], s[28:29], 12
	s_add_u32 s28, s94, s28
	s_addc_u32 s29, s95, s29
	s_cbranch_execnz .LBB0_153
